# row phases (finish-layer modes): gate and g_post vector loads of a row all issued before the first chunk with counted vmcnt
# speedup vs baseline: 1.0087x; 1.0087x over previous
.LBB0_177:
	v_ashrrev_i32_e32 v37, 12, v72
	v_add_u32_e32 v37, 1, v37
	v_cndmask_b32_e64 v39, v37, 0, s[0:1]
	s_and_b64 vcc, exec, s[40:41]
	v_lshlrev_b32_e32 v78, 2, v36
	v_lshlrev_b32_e32 v76, 2, v38
	v_lshlrev_b32_e32 v74, 2, v40
	v_lshlrev_b32_e32 v72, 2, v42
	s_cbranch_vccnz .LBB0_179
	v_fmamk_f32 v41, v35, 0x3a800000, v148
	v_cmp_gt_f32_e32 vcc, s98, v41
	v_mul_f32_e32 v43, 0x4b800000, v41
	s_mul_i32 s0, s4, 9
	v_cndmask_b32_e32 v41, v41, v43, vcc
	v_rsq_f32_e32 v41, v41
	v_mov_b64_e32 v[90:91], s[30:31]
	v_mov_b32_e32 v79, v0
	v_and_b32_e32 v101, 0xffff0000, v68
	v_mul_f32_e32 v43, 0x45800000, v41
	v_cndmask_b32_e32 v88, v41, v43, vcc
	v_add_u32_e32 v41, s0, v39
	v_mad_i64_i32 v[90:91], s[0:1], v41, s16, v[90:91]
	s_mov_b64 s[0:1], 0x2000
	s_nop 0
	v_lshl_add_u64 v[90:91], v[90:91], 0, s[0:1]
	v_mov_b32_e32 v77, v0
	v_mov_b32_e32 v75, v0
	v_mov_b32_e32 v73, v0
	v_lshl_add_u64 v[92:93], v[90:91], 0, v[78:79]
	global_load_dwordx4 v[152:155], v[92:93], off
	global_load_dwordx4 v[168:171], v[46:47], off
	v_lshl_add_u64 v[92:93], v[90:91], 0, v[76:77]
	global_load_dwordx4 v[156:159], v[92:93], off
	global_load_dwordx4 v[234:237], v[46:47], off offset:1024
	v_lshl_add_u64 v[92:93], v[90:91], 0, v[74:75]
	global_load_dwordx4 v[160:163], v[92:93], off
	global_load_dwordx4 v[238:241], v[46:47], off offset:2048
	v_lshl_add_u64 v[92:93], v[90:91], 0, v[72:73]
	global_load_dwordx4 v[164:167], v[92:93], off
	global_load_dwordx4 v[250:253], v[46:47], off offset:3072
	s_nop 0
	v_lshlrev_b32_e32 v100, 16, v68
	v_mov_b32_e32 v81, v0
	v_lshl_add_u64 v[86:87], v[86:87], 0, v[80:81]
	v_mov_b32_e32 v77, v0
	v_mov_b32_e32 v75, v0
	v_mov_b32_e32 v73, v0
	s_waitcnt vmcnt(7)
	v_pk_mul_f32 v[92:93], v[152:153], v[100:101]
	s_nop 0
	v_pk_mul_f32 v[92:93], v[88:89], v[92:93] op_sel_hi:[0,1]
	s_waitcnt vmcnt(6)
	v_pk_fma_f32 v[30:31], v[92:93], v[168:169], v[30:31]
	v_and_b32_e32 v93, 0xffff0000, v69
	v_lshlrev_b32_e32 v92, 16, v69
	v_pk_mul_f32 v[92:93], v[154:155], v[92:93]
	v_and_b32_e32 v101, 0xffff0000, v66
	v_pk_mul_f32 v[92:93], v[88:89], v[92:93] op_sel_hi:[0,1]
	v_pk_fma_f32 v[32:33], v[92:93], v[170:171], v[32:33]
	global_store_dwordx4 v[86:87], v[30:33], off nt
	s_nop 0
	v_lshlrev_b32_e32 v100, 16, v66
	s_waitcnt vmcnt(6)
	v_pk_mul_f32 v[92:93], v[156:157], v[100:101]
	s_nop 0
	v_pk_mul_f32 v[92:93], v[88:89], v[92:93] op_sel_hi:[0,1]
	s_waitcnt vmcnt(5)
	v_pk_fma_f32 v[26:27], v[92:93], v[234:235], v[26:27]
	v_and_b32_e32 v93, 0xffff0000, v67
	v_lshlrev_b32_e32 v92, 16, v67
	v_pk_mul_f32 v[92:93], v[158:159], v[92:93]
	v_and_b32_e32 v101, 0xffff0000, v64
	v_pk_mul_f32 v[92:93], v[88:89], v[92:93] op_sel_hi:[0,1]
	v_pk_fma_f32 v[28:29], v[92:93], v[236:237], v[28:29]
	global_store_dwordx4 v[86:87], v[26:29], off offset:1024 nt
	s_nop 0
	v_lshlrev_b32_e32 v100, 16, v64
	v_lshl_add_u64 v[90:91], v[90:91], 0, v[72:73]
	s_waitcnt vmcnt(5)
	v_pk_mul_f32 v[92:93], v[160:161], v[100:101]
	s_nop 0
	v_pk_mul_f32 v[92:93], v[88:89], v[92:93] op_sel_hi:[0,1]
	s_waitcnt vmcnt(4)
	v_pk_fma_f32 v[22:23], v[92:93], v[238:239], v[22:23]
	v_and_b32_e32 v93, 0xffff0000, v65
	v_lshlrev_b32_e32 v92, 16, v65
	v_pk_mul_f32 v[92:93], v[162:163], v[92:93]
	s_nop 0
	v_pk_mul_f32 v[92:93], v[88:89], v[92:93] op_sel_hi:[0,1]
	v_pk_fma_f32 v[24:25], v[92:93], v[240:241], v[24:25]
	global_store_dwordx4 v[86:87], v[22:25], off offset:2048 nt
	s_nop 0
	v_and_b32_e32 v99, 0xffff0000, v62
	v_lshlrev_b32_e32 v98, 16, v62
	s_waitcnt vmcnt(4)
	v_pk_mul_f32 v[90:91], v[164:165], v[98:99]
	s_nop 0
	v_pk_mul_f32 v[90:91], v[88:89], v[90:91] op_sel_hi:[0,1]
	s_waitcnt vmcnt(3)
	v_pk_fma_f32 v[18:19], v[90:91], v[250:251], v[18:19]
	v_and_b32_e32 v91, 0xffff0000, v63
	v_lshlrev_b32_e32 v90, 16, v63
	v_pk_mul_f32 v[90:91], v[166:167], v[90:91]
	s_nop 0
	v_pk_mul_f32 v[88:89], v[88:89], v[90:91] op_sel_hi:[0,1]
	v_pk_fma_f32 v[20:21], v[88:89], v[252:253], v[20:21]
	global_store_dwordx4 v[86:87], v[18:21], off offset:3072 nt

.LBB0_183:
	v_fmamk_f32 v18, v1, 0x3a800000, v148
	v_cmp_gt_f32_e32 vcc, s98, v18
	v_mul_f32_e32 v20, 0x4b800000, v18
	s_mul_i32 s0, s4, 9
	v_cndmask_b32_e32 v18, v18, v20, vcc
	v_rsq_f32_e32 v18, v18
	v_add_u32_e32 v22, s0, v19
	v_mov_b32_e32 v79, v0
	v_and_b32_e32 v33, 0xffff0000, v60
	v_mul_f32_e32 v20, 0x45800000, v18
	v_cndmask_b32_e32 v18, v18, v20, vcc
	v_mov_b64_e32 v[20:21], s[30:31]
	v_mad_i64_i32 v[20:21], s[0:1], v22, s16, v[20:21]
	s_mov_b64 s[0:1], 0x2000
	s_nop 0
	v_lshl_add_u64 v[22:23], v[20:21], 0, s[0:1]
	v_mov_b32_e32 v77, v0
	v_mov_b32_e32 v75, v0
	v_mov_b32_e32 v73, v0
	v_lshl_add_u64 v[24:25], v[22:23], 0, v[78:79]
	global_load_dwordx4 v[152:155], v[24:25], off
	global_load_dwordx4 v[168:171], v[46:47], off
	v_lshl_add_u64 v[24:25], v[22:23], 0, v[76:77]
	global_load_dwordx4 v[156:159], v[24:25], off
	global_load_dwordx4 v[234:237], v[46:47], off offset:1024
	v_lshl_add_u64 v[24:25], v[22:23], 0, v[74:75]
	global_load_dwordx4 v[160:163], v[24:25], off
	global_load_dwordx4 v[238:241], v[46:47], off offset:2048
	v_lshl_add_u64 v[24:25], v[22:23], 0, v[72:73]
	global_load_dwordx4 v[164:167], v[24:25], off
	global_load_dwordx4 v[250:253], v[46:47], off offset:3072
	s_nop 0
	v_lshlrev_b32_e32 v32, 16, v60
	v_mov_b32_e32 v81, v0
	v_lshl_add_u64 v[20:21], v[82:83], 0, v[80:81]
	v_mov_b32_e32 v77, v0
	v_mov_b32_e32 v75, v0
	v_mov_b32_e32 v73, v0
	s_waitcnt vmcnt(7)
	v_pk_mul_f32 v[24:25], v[152:153], v[32:33]
	s_nop 0
	v_pk_mul_f32 v[24:25], v[18:19], v[24:25] op_sel_hi:[0,1]
	s_waitcnt vmcnt(6)
	v_pk_fma_f32 v[14:15], v[24:25], v[168:169], v[14:15]
	v_and_b32_e32 v25, 0xffff0000, v61
	v_lshlrev_b32_e32 v24, 16, v61
	v_pk_mul_f32 v[24:25], v[154:155], v[24:25]
	v_and_b32_e32 v33, 0xffff0000, v58
	v_pk_mul_f32 v[24:25], v[18:19], v[24:25] op_sel_hi:[0,1]
	v_pk_fma_f32 v[16:17], v[24:25], v[170:171], v[16:17]
	global_store_dwordx4 v[20:21], v[14:17], off nt
	s_nop 0
	v_lshlrev_b32_e32 v32, 16, v58
	s_waitcnt vmcnt(6)
	v_pk_mul_f32 v[24:25], v[156:157], v[32:33]
	s_nop 0
	v_pk_mul_f32 v[24:25], v[18:19], v[24:25] op_sel_hi:[0,1]
	s_waitcnt vmcnt(5)
	v_pk_fma_f32 v[10:11], v[24:25], v[234:235], v[10:11]
	v_and_b32_e32 v25, 0xffff0000, v59
	v_lshlrev_b32_e32 v24, 16, v59
	v_pk_mul_f32 v[24:25], v[158:159], v[24:25]
	v_and_b32_e32 v33, 0xffff0000, v56
	v_pk_mul_f32 v[24:25], v[18:19], v[24:25] op_sel_hi:[0,1]
	v_pk_fma_f32 v[12:13], v[24:25], v[236:237], v[12:13]
	global_store_dwordx4 v[20:21], v[10:13], off offset:1024 nt
	s_nop 0
	v_lshlrev_b32_e32 v32, 16, v56
	v_lshl_add_u64 v[22:23], v[22:23], 0, v[72:73]
	s_waitcnt vmcnt(5)
	v_pk_mul_f32 v[24:25], v[160:161], v[32:33]
	s_nop 0
	v_pk_mul_f32 v[24:25], v[18:19], v[24:25] op_sel_hi:[0,1]
	s_waitcnt vmcnt(4)
	v_pk_fma_f32 v[6:7], v[24:25], v[238:239], v[6:7]
	v_and_b32_e32 v25, 0xffff0000, v57
	v_lshlrev_b32_e32 v24, 16, v57
	v_pk_mul_f32 v[24:25], v[162:163], v[24:25]
	s_nop 0
	v_pk_mul_f32 v[24:25], v[18:19], v[24:25] op_sel_hi:[0,1]
	v_pk_fma_f32 v[8:9], v[24:25], v[240:241], v[8:9]
	global_store_dwordx4 v[20:21], v[6:9], off offset:2048 nt
	s_nop 0
	v_and_b32_e32 v31, 0xffff0000, v54
	v_lshlrev_b32_e32 v30, 16, v54
	s_waitcnt vmcnt(4)
	v_pk_mul_f32 v[22:23], v[164:165], v[30:31]
	s_nop 0
	v_pk_mul_f32 v[22:23], v[18:19], v[22:23] op_sel_hi:[0,1]
	s_waitcnt vmcnt(3)
	v_pk_fma_f32 v[2:3], v[22:23], v[250:251], v[2:3]
	v_and_b32_e32 v23, 0xffff0000, v55
	v_lshlrev_b32_e32 v22, 16, v55
	v_pk_mul_f32 v[22:23], v[166:167], v[22:23]
	s_nop 0
	v_pk_mul_f32 v[22:23], v[18:19], v[22:23] op_sel_hi:[0,1]
	v_pk_fma_f32 v[4:5], v[22:23], v[252:253], v[4:5]
	global_store_dwordx4 v[20:21], v[2:5], off offset:3072 nt
	s_and_b64 vcc, exec, s[44:45]
	s_cbranch_vccnz .LBB0_164
